# v012 + hand-written P1 EpiZ epilogue: 3 straight-line variants (rope with all cos/sin rows loaded at once and packed-f32 rotation, plain, sigmoid gates), bf16 packed in place
# baseline (speedup 1.0000x reference)
.LBB0_161:
	v_lshl_add_u32 v148, s6, 8, v187
	v_ashrrev_i32_e32 v149, 31, v148
	v_lshl_add_u64 v[146:147], v[148:149], 2, s[84:85]
	global_load_dword v150, v[146:147], off
	global_load_dword v151, v[146:147], off offset:64
	global_load_dword v152, v[146:147], off offset:128
	global_load_dword v153, v[146:147], off offset:192
	global_load_dword v154, v[146:147], off offset:512
	global_load_dword v155, v[146:147], off offset:576
	global_load_dword v156, v[146:147], off offset:640
	global_load_dword v157, v[146:147], off offset:704
	v_lshl_or_b32 v160, s4, 8, v189
	v_mov_b32_e32 v161, 0
	s_cmp_lt_i32 s4, 4
	s_cbranch_scc1 .Lz_rope
	s_cmp_lt_i32 s4, 12
	s_cbranch_scc1 .Lz_plain
	s_sub_i32 s5, s4, 12
	s_lshl_b32 s5, s5, 9
	v_lshl_add_u32 v160, v189, 1, s5
	v_lshlrev_b64 v[158:159], 12, v[148:149]
	v_lshl_add_u64 v[160:161], s[8:9], 0, v[160:161]
	v_lshl_add_u64 v[158:159], v[158:159], 0, v[160:161]
	s_mov_b64 s[28:29], 0x10000
	s_mov_b64 s[30:31], 0x50000
	s_waitcnt vmcnt(0)
	v_mul_f32_e32 v150, 0xbfb8aa3b, v150
	v_mul_f32_e32 v151, 0xbfb8aa3b, v151
	v_mul_f32_e32 v152, 0xbfb8aa3b, v152
	v_mul_f32_e32 v153, 0xbfb8aa3b, v153
	v_mul_f32_e32 v154, 0xbfb8aa3b, v154
	v_mul_f32_e32 v155, 0xbfb8aa3b, v155
	v_mul_f32_e32 v156, 0xbfb8aa3b, v156
	v_mul_f32_e32 v157, 0xbfb8aa3b, v157
	v_pk_mul_f32 v[124:125], v[124:125], v[150:151] op_sel_hi:[1,0]
	v_pk_mul_f32 v[126:127], v[126:127], v[150:151] op_sel_hi:[1,0]
	v_pk_mul_f32 v[120:121], v[120:121], v[150:151] op_sel_hi:[1,0]
	v_pk_mul_f32 v[122:123], v[122:123], v[150:151] op_sel_hi:[1,0]
	v_exp_f32_e32 v120, v120
	v_exp_f32_e32 v121, v121
	v_exp_f32_e32 v122, v122
	v_exp_f32_e32 v123, v123
	v_exp_f32_e32 v124, v124
	v_exp_f32_e32 v125, v125
	v_exp_f32_e32 v126, v126
	v_exp_f32_e32 v127, v127
	v_pk_add_f32 v[120:121], v[120:121], 1.0 op_sel_hi:[1,0]
	v_pk_add_f32 v[122:123], v[122:123], 1.0 op_sel_hi:[1,0]
	v_pk_add_f32 v[124:125], v[124:125], 1.0 op_sel_hi:[1,0]
	v_pk_add_f32 v[126:127], v[126:127], 1.0 op_sel_hi:[1,0]
	v_rcp_f32_e32 v120, v120
	v_rcp_f32_e32 v121, v121
	v_rcp_f32_e32 v122, v122
	v_rcp_f32_e32 v123, v123
	v_rcp_f32_e32 v124, v124
	v_rcp_f32_e32 v125, v125
	v_rcp_f32_e32 v126, v126
	v_rcp_f32_e32 v127, v127
	v_cvt_pk_bf16_f32 v124, v124, v125
	v_cvt_pk_bf16_f32 v125, v126, v127
	v_cvt_pk_bf16_f32 v126, v120, v121
	v_cvt_pk_bf16_f32 v127, v122, v123
	global_store_dwordx4 v[158:159], v[124:127], off
	v_pk_mul_f32 v[116:117], v[116:117], v[150:151] op_sel_hi:[1,0]
	v_pk_mul_f32 v[118:119], v[118:119], v[150:151] op_sel_hi:[1,0]
	v_pk_mul_f32 v[112:113], v[112:113], v[150:151] op_sel_hi:[1,0]
	v_pk_mul_f32 v[114:115], v[114:115], v[150:151] op_sel_hi:[1,0]
	v_exp_f32_e32 v112, v112
	v_exp_f32_e32 v113, v113
	v_exp_f32_e32 v114, v114
	v_exp_f32_e32 v115, v115
	v_exp_f32_e32 v116, v116
	v_exp_f32_e32 v117, v117
	v_exp_f32_e32 v118, v118
	v_exp_f32_e32 v119, v119
	v_pk_add_f32 v[112:113], v[112:113], 1.0 op_sel_hi:[1,0]
	v_pk_add_f32 v[114:115], v[114:115], 1.0 op_sel_hi:[1,0]
	v_pk_add_f32 v[116:117], v[116:117], 1.0 op_sel_hi:[1,0]
	v_pk_add_f32 v[118:119], v[118:119], 1.0 op_sel_hi:[1,0]
	v_rcp_f32_e32 v112, v112
	v_rcp_f32_e32 v113, v113
	v_rcp_f32_e32 v114, v114
	v_rcp_f32_e32 v115, v115
	v_rcp_f32_e32 v116, v116
	v_rcp_f32_e32 v117, v117
	v_rcp_f32_e32 v118, v118
	v_rcp_f32_e32 v119, v119
	v_cvt_pk_bf16_f32 v116, v116, v117
	v_cvt_pk_bf16_f32 v117, v118, v119
	v_cvt_pk_bf16_f32 v118, v112, v113
	v_cvt_pk_bf16_f32 v119, v114, v115
	global_store_dwordx4 v[158:159], v[116:119], off offset:256
	v_lshl_add_u64 v[158:159], v[158:159], 0, s[28:29]
	v_pk_mul_f32 v[108:109], v[108:109], v[150:151] op_sel:[0,1] op_sel_hi:[1,1]
	v_pk_mul_f32 v[110:111], v[110:111], v[150:151] op_sel:[0,1] op_sel_hi:[1,1]
	v_pk_mul_f32 v[104:105], v[104:105], v[150:151] op_sel:[0,1] op_sel_hi:[1,1]
	v_pk_mul_f32 v[106:107], v[106:107], v[150:151] op_sel:[0,1] op_sel_hi:[1,1]
	v_exp_f32_e32 v104, v104
	v_exp_f32_e32 v105, v105
	v_exp_f32_e32 v106, v106
	v_exp_f32_e32 v107, v107
	v_exp_f32_e32 v108, v108
	v_exp_f32_e32 v109, v109
	v_exp_f32_e32 v110, v110
	v_exp_f32_e32 v111, v111
	v_pk_add_f32 v[104:105], v[104:105], 1.0 op_sel_hi:[1,0]
	v_pk_add_f32 v[106:107], v[106:107], 1.0 op_sel_hi:[1,0]
	v_pk_add_f32 v[108:109], v[108:109], 1.0 op_sel_hi:[1,0]
	v_pk_add_f32 v[110:111], v[110:111], 1.0 op_sel_hi:[1,0]
	v_rcp_f32_e32 v104, v104
	v_rcp_f32_e32 v105, v105
	v_rcp_f32_e32 v106, v106
	v_rcp_f32_e32 v107, v107
	v_rcp_f32_e32 v108, v108
	v_rcp_f32_e32 v109, v109
	v_rcp_f32_e32 v110, v110
	v_rcp_f32_e32 v111, v111
	v_cvt_pk_bf16_f32 v108, v108, v109
	v_cvt_pk_bf16_f32 v109, v110, v111
	v_cvt_pk_bf16_f32 v110, v104, v105
	v_cvt_pk_bf16_f32 v111, v106, v107
	global_store_dwordx4 v[158:159], v[108:111], off
	v_pk_mul_f32 v[100:101], v[100:101], v[150:151] op_sel:[0,1] op_sel_hi:[1,1]
	v_pk_mul_f32 v[102:103], v[102:103], v[150:151] op_sel:[0,1] op_sel_hi:[1,1]
	v_pk_mul_f32 v[96:97], v[96:97], v[150:151] op_sel:[0,1] op_sel_hi:[1,1]
	v_pk_mul_f32 v[98:99], v[98:99], v[150:151] op_sel:[0,1] op_sel_hi:[1,1]
	v_exp_f32_e32 v96, v96
	v_exp_f32_e32 v97, v97
	v_exp_f32_e32 v98, v98
	v_exp_f32_e32 v99, v99
	v_exp_f32_e32 v100, v100
	v_exp_f32_e32 v101, v101
	v_exp_f32_e32 v102, v102
	v_exp_f32_e32 v103, v103
	v_pk_add_f32 v[96:97], v[96:97], 1.0 op_sel_hi:[1,0]
	v_pk_add_f32 v[98:99], v[98:99], 1.0 op_sel_hi:[1,0]
	v_pk_add_f32 v[100:101], v[100:101], 1.0 op_sel_hi:[1,0]
	v_pk_add_f32 v[102:103], v[102:103], 1.0 op_sel_hi:[1,0]
	v_rcp_f32_e32 v96, v96
	v_rcp_f32_e32 v97, v97
	v_rcp_f32_e32 v98, v98
	v_rcp_f32_e32 v99, v99
	v_rcp_f32_e32 v100, v100
	v_rcp_f32_e32 v101, v101
	v_rcp_f32_e32 v102, v102
	v_rcp_f32_e32 v103, v103
	v_cvt_pk_bf16_f32 v100, v100, v101
	v_cvt_pk_bf16_f32 v101, v102, v103
	v_cvt_pk_bf16_f32 v102, v96, v97
	v_cvt_pk_bf16_f32 v103, v98, v99
	global_store_dwordx4 v[158:159], v[100:103], off offset:256
	v_lshl_add_u64 v[158:159], v[158:159], 0, s[28:29]
	v_pk_mul_f32 v[92:93], v[92:93], v[152:153] op_sel_hi:[1,0]
	v_pk_mul_f32 v[94:95], v[94:95], v[152:153] op_sel_hi:[1,0]
	v_pk_mul_f32 v[88:89], v[88:89], v[152:153] op_sel_hi:[1,0]
	v_pk_mul_f32 v[90:91], v[90:91], v[152:153] op_sel_hi:[1,0]
	v_exp_f32_e32 v88, v88
	v_exp_f32_e32 v89, v89
	v_exp_f32_e32 v90, v90
	v_exp_f32_e32 v91, v91
	v_exp_f32_e32 v92, v92
	v_exp_f32_e32 v93, v93
	v_exp_f32_e32 v94, v94
	v_exp_f32_e32 v95, v95
	v_pk_add_f32 v[88:89], v[88:89], 1.0 op_sel_hi:[1,0]
	v_pk_add_f32 v[90:91], v[90:91], 1.0 op_sel_hi:[1,0]
	v_pk_add_f32 v[92:93], v[92:93], 1.0 op_sel_hi:[1,0]
	v_pk_add_f32 v[94:95], v[94:95], 1.0 op_sel_hi:[1,0]
	v_rcp_f32_e32 v88, v88
	v_rcp_f32_e32 v89, v89
	v_rcp_f32_e32 v90, v90
	v_rcp_f32_e32 v91, v91
	v_rcp_f32_e32 v92, v92
	v_rcp_f32_e32 v93, v93
	v_rcp_f32_e32 v94, v94
	v_rcp_f32_e32 v95, v95
	v_cvt_pk_bf16_f32 v92, v92, v93
	v_cvt_pk_bf16_f32 v93, v94, v95
	v_cvt_pk_bf16_f32 v94, v88, v89
	v_cvt_pk_bf16_f32 v95, v90, v91
	global_store_dwordx4 v[158:159], v[92:95], off
	v_pk_mul_f32 v[84:85], v[84:85], v[152:153] op_sel_hi:[1,0]
	v_pk_mul_f32 v[86:87], v[86:87], v[152:153] op_sel_hi:[1,0]
	v_pk_mul_f32 v[80:81], v[80:81], v[152:153] op_sel_hi:[1,0]
	v_pk_mul_f32 v[82:83], v[82:83], v[152:153] op_sel_hi:[1,0]
	v_exp_f32_e32 v80, v80
	v_exp_f32_e32 v81, v81
	v_exp_f32_e32 v82, v82
	v_exp_f32_e32 v83, v83
	v_exp_f32_e32 v84, v84
	v_exp_f32_e32 v85, v85
	v_exp_f32_e32 v86, v86
	v_exp_f32_e32 v87, v87
	v_pk_add_f32 v[80:81], v[80:81], 1.0 op_sel_hi:[1,0]
	v_pk_add_f32 v[82:83], v[82:83], 1.0 op_sel_hi:[1,0]
	v_pk_add_f32 v[84:85], v[84:85], 1.0 op_sel_hi:[1,0]
	v_pk_add_f32 v[86:87], v[86:87], 1.0 op_sel_hi:[1,0]
	v_rcp_f32_e32 v80, v80
	v_rcp_f32_e32 v81, v81
	v_rcp_f32_e32 v82, v82
	v_rcp_f32_e32 v83, v83
	v_rcp_f32_e32 v84, v84
	v_rcp_f32_e32 v85, v85
	v_rcp_f32_e32 v86, v86
	v_rcp_f32_e32 v87, v87
	v_cvt_pk_bf16_f32 v84, v84, v85
	v_cvt_pk_bf16_f32 v85, v86, v87
	v_cvt_pk_bf16_f32 v86, v80, v81
	v_cvt_pk_bf16_f32 v87, v82, v83
	global_store_dwordx4 v[158:159], v[84:87], off offset:256
	v_lshl_add_u64 v[158:159], v[158:159], 0, s[28:29]
	v_pk_mul_f32 v[76:77], v[76:77], v[152:153] op_sel:[0,1] op_sel_hi:[1,1]
	v_pk_mul_f32 v[78:79], v[78:79], v[152:153] op_sel:[0,1] op_sel_hi:[1,1]
	v_pk_mul_f32 v[72:73], v[72:73], v[152:153] op_sel:[0,1] op_sel_hi:[1,1]
	v_pk_mul_f32 v[74:75], v[74:75], v[152:153] op_sel:[0,1] op_sel_hi:[1,1]
	v_exp_f32_e32 v72, v72
	v_exp_f32_e32 v73, v73
	v_exp_f32_e32 v74, v74
	v_exp_f32_e32 v75, v75
	v_exp_f32_e32 v76, v76
	v_exp_f32_e32 v77, v77
	v_exp_f32_e32 v78, v78
	v_exp_f32_e32 v79, v79
	v_pk_add_f32 v[72:73], v[72:73], 1.0 op_sel_hi:[1,0]
	v_pk_add_f32 v[74:75], v[74:75], 1.0 op_sel_hi:[1,0]
	v_pk_add_f32 v[76:77], v[76:77], 1.0 op_sel_hi:[1,0]
	v_pk_add_f32 v[78:79], v[78:79], 1.0 op_sel_hi:[1,0]
	v_rcp_f32_e32 v72, v72
	v_rcp_f32_e32 v73, v73
	v_rcp_f32_e32 v74, v74
	v_rcp_f32_e32 v75, v75
	v_rcp_f32_e32 v76, v76
	v_rcp_f32_e32 v77, v77
	v_rcp_f32_e32 v78, v78
	v_rcp_f32_e32 v79, v79
	v_cvt_pk_bf16_f32 v76, v76, v77
	v_cvt_pk_bf16_f32 v77, v78, v79
	v_cvt_pk_bf16_f32 v78, v72, v73
	v_cvt_pk_bf16_f32 v79, v74, v75
	global_store_dwordx4 v[158:159], v[76:79], off
	v_pk_mul_f32 v[68:69], v[68:69], v[152:153] op_sel:[0,1] op_sel_hi:[1,1]
	v_pk_mul_f32 v[70:71], v[70:71], v[152:153] op_sel:[0,1] op_sel_hi:[1,1]
	v_pk_mul_f32 v[64:65], v[64:65], v[152:153] op_sel:[0,1] op_sel_hi:[1,1]
	v_pk_mul_f32 v[66:67], v[66:67], v[152:153] op_sel:[0,1] op_sel_hi:[1,1]
	v_exp_f32_e32 v64, v64
	v_exp_f32_e32 v65, v65
	v_exp_f32_e32 v66, v66
	v_exp_f32_e32 v67, v67
	v_exp_f32_e32 v68, v68
	v_exp_f32_e32 v69, v69
	v_exp_f32_e32 v70, v70
	v_exp_f32_e32 v71, v71
	v_pk_add_f32 v[64:65], v[64:65], 1.0 op_sel_hi:[1,0]
	v_pk_add_f32 v[66:67], v[66:67], 1.0 op_sel_hi:[1,0]
	v_pk_add_f32 v[68:69], v[68:69], 1.0 op_sel_hi:[1,0]
	v_pk_add_f32 v[70:71], v[70:71], 1.0 op_sel_hi:[1,0]
	v_rcp_f32_e32 v64, v64
	v_rcp_f32_e32 v65, v65
	v_rcp_f32_e32 v66, v66
	v_rcp_f32_e32 v67, v67
	v_rcp_f32_e32 v68, v68
	v_rcp_f32_e32 v69, v69
	v_rcp_f32_e32 v70, v70
	v_rcp_f32_e32 v71, v71
	v_cvt_pk_bf16_f32 v68, v68, v69
	v_cvt_pk_bf16_f32 v69, v70, v71
	v_cvt_pk_bf16_f32 v70, v64, v65
	v_cvt_pk_bf16_f32 v71, v66, v67
	global_store_dwordx4 v[158:159], v[68:71], off offset:256
	v_lshl_add_u64 v[158:159], v[158:159], 0, s[30:31]
	v_pk_mul_f32 v[60:61], v[60:61], v[154:155] op_sel_hi:[1,0]
	v_pk_mul_f32 v[62:63], v[62:63], v[154:155] op_sel_hi:[1,0]
	v_pk_mul_f32 v[56:57], v[56:57], v[154:155] op_sel_hi:[1,0]
	v_pk_mul_f32 v[58:59], v[58:59], v[154:155] op_sel_hi:[1,0]
	v_exp_f32_e32 v56, v56
	v_exp_f32_e32 v57, v57
	v_exp_f32_e32 v58, v58
	v_exp_f32_e32 v59, v59
	v_exp_f32_e32 v60, v60
	v_exp_f32_e32 v61, v61
	v_exp_f32_e32 v62, v62
	v_exp_f32_e32 v63, v63
	v_pk_add_f32 v[56:57], v[56:57], 1.0 op_sel_hi:[1,0]
	v_pk_add_f32 v[58:59], v[58:59], 1.0 op_sel_hi:[1,0]
	v_pk_add_f32 v[60:61], v[60:61], 1.0 op_sel_hi:[1,0]
	v_pk_add_f32 v[62:63], v[62:63], 1.0 op_sel_hi:[1,0]
	v_rcp_f32_e32 v56, v56
	v_rcp_f32_e32 v57, v57
	v_rcp_f32_e32 v58, v58
	v_rcp_f32_e32 v59, v59
	v_rcp_f32_e32 v60, v60
	v_rcp_f32_e32 v61, v61
	v_rcp_f32_e32 v62, v62
	v_rcp_f32_e32 v63, v63
	v_cvt_pk_bf16_f32 v60, v60, v61
	v_cvt_pk_bf16_f32 v61, v62, v63
	v_cvt_pk_bf16_f32 v62, v56, v57
	v_cvt_pk_bf16_f32 v63, v58, v59
	global_store_dwordx4 v[158:159], v[60:63], off
	v_pk_mul_f32 v[52:53], v[52:53], v[154:155] op_sel_hi:[1,0]
	v_pk_mul_f32 v[54:55], v[54:55], v[154:155] op_sel_hi:[1,0]
	v_pk_mul_f32 v[48:49], v[48:49], v[154:155] op_sel_hi:[1,0]
	v_pk_mul_f32 v[50:51], v[50:51], v[154:155] op_sel_hi:[1,0]
	v_exp_f32_e32 v48, v48
	v_exp_f32_e32 v49, v49
	v_exp_f32_e32 v50, v50
	v_exp_f32_e32 v51, v51
	v_exp_f32_e32 v52, v52
	v_exp_f32_e32 v53, v53
	v_exp_f32_e32 v54, v54
	v_exp_f32_e32 v55, v55
	v_pk_add_f32 v[48:49], v[48:49], 1.0 op_sel_hi:[1,0]
	v_pk_add_f32 v[50:51], v[50:51], 1.0 op_sel_hi:[1,0]
	v_pk_add_f32 v[52:53], v[52:53], 1.0 op_sel_hi:[1,0]
	v_pk_add_f32 v[54:55], v[54:55], 1.0 op_sel_hi:[1,0]
	v_rcp_f32_e32 v48, v48
	v_rcp_f32_e32 v49, v49
	v_rcp_f32_e32 v50, v50
	v_rcp_f32_e32 v51, v51
	v_rcp_f32_e32 v52, v52
	v_rcp_f32_e32 v53, v53
	v_rcp_f32_e32 v54, v54
	v_rcp_f32_e32 v55, v55
	v_cvt_pk_bf16_f32 v52, v52, v53
	v_cvt_pk_bf16_f32 v53, v54, v55
	v_cvt_pk_bf16_f32 v54, v48, v49
	v_cvt_pk_bf16_f32 v55, v50, v51
	global_store_dwordx4 v[158:159], v[52:55], off offset:256
	v_lshl_add_u64 v[158:159], v[158:159], 0, s[28:29]
	v_pk_mul_f32 v[44:45], v[44:45], v[154:155] op_sel:[0,1] op_sel_hi:[1,1]
	v_pk_mul_f32 v[46:47], v[46:47], v[154:155] op_sel:[0,1] op_sel_hi:[1,1]
	v_pk_mul_f32 v[40:41], v[40:41], v[154:155] op_sel:[0,1] op_sel_hi:[1,1]
	v_pk_mul_f32 v[42:43], v[42:43], v[154:155] op_sel:[0,1] op_sel_hi:[1,1]
	v_exp_f32_e32 v40, v40
	v_exp_f32_e32 v41, v41
	v_exp_f32_e32 v42, v42
	v_exp_f32_e32 v43, v43
	v_exp_f32_e32 v44, v44
	v_exp_f32_e32 v45, v45
	v_exp_f32_e32 v46, v46
	v_exp_f32_e32 v47, v47
	v_pk_add_f32 v[40:41], v[40:41], 1.0 op_sel_hi:[1,0]
	v_pk_add_f32 v[42:43], v[42:43], 1.0 op_sel_hi:[1,0]
	v_pk_add_f32 v[44:45], v[44:45], 1.0 op_sel_hi:[1,0]
	v_pk_add_f32 v[46:47], v[46:47], 1.0 op_sel_hi:[1,0]
	v_rcp_f32_e32 v40, v40
	v_rcp_f32_e32 v41, v41
	v_rcp_f32_e32 v42, v42
	v_rcp_f32_e32 v43, v43
	v_rcp_f32_e32 v44, v44
	v_rcp_f32_e32 v45, v45
	v_rcp_f32_e32 v46, v46
	v_rcp_f32_e32 v47, v47
	v_cvt_pk_bf16_f32 v44, v44, v45
	v_cvt_pk_bf16_f32 v45, v46, v47
	v_cvt_pk_bf16_f32 v46, v40, v41
	v_cvt_pk_bf16_f32 v47, v42, v43
	global_store_dwordx4 v[158:159], v[44:47], off
	v_pk_mul_f32 v[36:37], v[36:37], v[154:155] op_sel:[0,1] op_sel_hi:[1,1]
	v_pk_mul_f32 v[38:39], v[38:39], v[154:155] op_sel:[0,1] op_sel_hi:[1,1]
	v_pk_mul_f32 v[32:33], v[32:33], v[154:155] op_sel:[0,1] op_sel_hi:[1,1]
	v_pk_mul_f32 v[34:35], v[34:35], v[154:155] op_sel:[0,1] op_sel_hi:[1,1]
	v_exp_f32_e32 v32, v32
	v_exp_f32_e32 v33, v33
	v_exp_f32_e32 v34, v34
	v_exp_f32_e32 v35, v35
	v_exp_f32_e32 v36, v36
	v_exp_f32_e32 v37, v37
	v_exp_f32_e32 v38, v38
	v_exp_f32_e32 v39, v39
	v_pk_add_f32 v[32:33], v[32:33], 1.0 op_sel_hi:[1,0]
	v_pk_add_f32 v[34:35], v[34:35], 1.0 op_sel_hi:[1,0]
	v_pk_add_f32 v[36:37], v[36:37], 1.0 op_sel_hi:[1,0]
	v_pk_add_f32 v[38:39], v[38:39], 1.0 op_sel_hi:[1,0]
	v_rcp_f32_e32 v32, v32
	v_rcp_f32_e32 v33, v33
	v_rcp_f32_e32 v34, v34
	v_rcp_f32_e32 v35, v35
	v_rcp_f32_e32 v36, v36
	v_rcp_f32_e32 v37, v37
	v_rcp_f32_e32 v38, v38
	v_rcp_f32_e32 v39, v39
	v_cvt_pk_bf16_f32 v36, v36, v37
	v_cvt_pk_bf16_f32 v37, v38, v39
	v_cvt_pk_bf16_f32 v38, v32, v33
	v_cvt_pk_bf16_f32 v39, v34, v35
	global_store_dwordx4 v[158:159], v[36:39], off offset:256
	v_lshl_add_u64 v[158:159], v[158:159], 0, s[28:29]
	v_pk_mul_f32 v[28:29], v[28:29], v[156:157] op_sel_hi:[1,0]
	v_pk_mul_f32 v[30:31], v[30:31], v[156:157] op_sel_hi:[1,0]
	v_pk_mul_f32 v[24:25], v[24:25], v[156:157] op_sel_hi:[1,0]
	v_pk_mul_f32 v[26:27], v[26:27], v[156:157] op_sel_hi:[1,0]
	v_exp_f32_e32 v24, v24
	v_exp_f32_e32 v25, v25
	v_exp_f32_e32 v26, v26
	v_exp_f32_e32 v27, v27
	v_exp_f32_e32 v28, v28
	v_exp_f32_e32 v29, v29
	v_exp_f32_e32 v30, v30
	v_exp_f32_e32 v31, v31
	v_pk_add_f32 v[24:25], v[24:25], 1.0 op_sel_hi:[1,0]
	v_pk_add_f32 v[26:27], v[26:27], 1.0 op_sel_hi:[1,0]
	v_pk_add_f32 v[28:29], v[28:29], 1.0 op_sel_hi:[1,0]
	v_pk_add_f32 v[30:31], v[30:31], 1.0 op_sel_hi:[1,0]
	v_rcp_f32_e32 v24, v24
	v_rcp_f32_e32 v25, v25
	v_rcp_f32_e32 v26, v26
	v_rcp_f32_e32 v27, v27
	v_rcp_f32_e32 v28, v28
	v_rcp_f32_e32 v29, v29
	v_rcp_f32_e32 v30, v30
	v_rcp_f32_e32 v31, v31
	v_cvt_pk_bf16_f32 v28, v28, v29
	v_cvt_pk_bf16_f32 v29, v30, v31
	v_cvt_pk_bf16_f32 v30, v24, v25
	v_cvt_pk_bf16_f32 v31, v26, v27
	global_store_dwordx4 v[158:159], v[28:31], off
	v_pk_mul_f32 v[20:21], v[20:21], v[156:157] op_sel_hi:[1,0]
	v_pk_mul_f32 v[22:23], v[22:23], v[156:157] op_sel_hi:[1,0]
	v_pk_mul_f32 v[16:17], v[16:17], v[156:157] op_sel_hi:[1,0]
	v_pk_mul_f32 v[18:19], v[18:19], v[156:157] op_sel_hi:[1,0]
	v_exp_f32_e32 v16, v16
	v_exp_f32_e32 v17, v17
	v_exp_f32_e32 v18, v18
	v_exp_f32_e32 v19, v19
	v_exp_f32_e32 v20, v20
	v_exp_f32_e32 v21, v21
	v_exp_f32_e32 v22, v22
	v_exp_f32_e32 v23, v23
	v_pk_add_f32 v[16:17], v[16:17], 1.0 op_sel_hi:[1,0]
	v_pk_add_f32 v[18:19], v[18:19], 1.0 op_sel_hi:[1,0]
	v_pk_add_f32 v[20:21], v[20:21], 1.0 op_sel_hi:[1,0]
	v_pk_add_f32 v[22:23], v[22:23], 1.0 op_sel_hi:[1,0]
	v_rcp_f32_e32 v16, v16
	v_rcp_f32_e32 v17, v17
	v_rcp_f32_e32 v18, v18
	v_rcp_f32_e32 v19, v19
	v_rcp_f32_e32 v20, v20
	v_rcp_f32_e32 v21, v21
	v_rcp_f32_e32 v22, v22
	v_rcp_f32_e32 v23, v23
	v_cvt_pk_bf16_f32 v20, v20, v21
	v_cvt_pk_bf16_f32 v21, v22, v23
	v_cvt_pk_bf16_f32 v22, v16, v17
	v_cvt_pk_bf16_f32 v23, v18, v19
	global_store_dwordx4 v[158:159], v[20:23], off offset:256
	v_lshl_add_u64 v[158:159], v[158:159], 0, s[28:29]
	v_pk_mul_f32 v[12:13], v[12:13], v[156:157] op_sel:[0,1] op_sel_hi:[1,1]
	v_pk_mul_f32 v[14:15], v[14:15], v[156:157] op_sel:[0,1] op_sel_hi:[1,1]
	v_pk_mul_f32 v[8:9], v[8:9], v[156:157] op_sel:[0,1] op_sel_hi:[1,1]
	v_pk_mul_f32 v[10:11], v[10:11], v[156:157] op_sel:[0,1] op_sel_hi:[1,1]
	v_exp_f32_e32 v8, v8
	v_exp_f32_e32 v9, v9
	v_exp_f32_e32 v10, v10
	v_exp_f32_e32 v11, v11
	v_exp_f32_e32 v12, v12
	v_exp_f32_e32 v13, v13
	v_exp_f32_e32 v14, v14
	v_exp_f32_e32 v15, v15
	v_pk_add_f32 v[8:9], v[8:9], 1.0 op_sel_hi:[1,0]
	v_pk_add_f32 v[10:11], v[10:11], 1.0 op_sel_hi:[1,0]
	v_pk_add_f32 v[12:13], v[12:13], 1.0 op_sel_hi:[1,0]
	v_pk_add_f32 v[14:15], v[14:15], 1.0 op_sel_hi:[1,0]
	v_rcp_f32_e32 v8, v8
	v_rcp_f32_e32 v9, v9
	v_rcp_f32_e32 v10, v10
	v_rcp_f32_e32 v11, v11
	v_rcp_f32_e32 v12, v12
	v_rcp_f32_e32 v13, v13
	v_rcp_f32_e32 v14, v14
	v_rcp_f32_e32 v15, v15
	v_cvt_pk_bf16_f32 v12, v12, v13
	v_cvt_pk_bf16_f32 v13, v14, v15
	v_cvt_pk_bf16_f32 v14, v8, v9
	v_cvt_pk_bf16_f32 v15, v10, v11
	global_store_dwordx4 v[158:159], v[12:15], off
	v_pk_mul_f32 v[4:5], v[4:5], v[156:157] op_sel:[0,1] op_sel_hi:[1,1]
	v_pk_mul_f32 v[6:7], v[6:7], v[156:157] op_sel:[0,1] op_sel_hi:[1,1]
	v_pk_mul_f32 v[0:1], v[0:1], v[156:157] op_sel:[0,1] op_sel_hi:[1,1]
	v_pk_mul_f32 v[2:3], v[2:3], v[156:157] op_sel:[0,1] op_sel_hi:[1,1]
	v_exp_f32_e32 v0, v0
	v_exp_f32_e32 v1, v1
	v_exp_f32_e32 v2, v2
	v_exp_f32_e32 v3, v3
	v_exp_f32_e32 v4, v4
	v_exp_f32_e32 v5, v5
	v_exp_f32_e32 v6, v6
	v_exp_f32_e32 v7, v7
	v_pk_add_f32 v[0:1], v[0:1], 1.0 op_sel_hi:[1,0]
	v_pk_add_f32 v[2:3], v[2:3], 1.0 op_sel_hi:[1,0]
	v_pk_add_f32 v[4:5], v[4:5], 1.0 op_sel_hi:[1,0]
	v_pk_add_f32 v[6:7], v[6:7], 1.0 op_sel_hi:[1,0]
	v_rcp_f32_e32 v0, v0
	v_rcp_f32_e32 v1, v1
	v_rcp_f32_e32 v2, v2
	v_rcp_f32_e32 v3, v3
	v_rcp_f32_e32 v4, v4
	v_rcp_f32_e32 v5, v5
	v_rcp_f32_e32 v6, v6
	v_rcp_f32_e32 v7, v7
	v_cvt_pk_bf16_f32 v4, v4, v5
	v_cvt_pk_bf16_f32 v5, v6, v7
	v_cvt_pk_bf16_f32 v6, v0, v1
	v_cvt_pk_bf16_f32 v7, v2, v3
	global_store_dwordx4 v[158:159], v[4:7], off offset:256
	s_branch .Lz_done
.Lz_plain:
	v_lshlrev_b32_e32 v160, 1, v160
	v_lshl_add_u64 v[160:161], s[10:11], 0, v[160:161]
	v_mad_i64_i32 v[158:159], vcc, v148, s62, v[160:161]
	s_mov_b64 s[28:29], 0x18000
	s_mov_b64 s[30:31], 0x78000
	s_waitcnt vmcnt(0)
	v_pk_mul_f32 v[124:125], v[124:125], v[150:151] op_sel_hi:[1,0]
	v_pk_mul_f32 v[126:127], v[126:127], v[150:151] op_sel_hi:[1,0]
	v_pk_mul_f32 v[120:121], v[120:121], v[150:151] op_sel_hi:[1,0]
	v_pk_mul_f32 v[122:123], v[122:123], v[150:151] op_sel_hi:[1,0]
	v_cvt_pk_bf16_f32 v124, v124, v125
	v_cvt_pk_bf16_f32 v125, v126, v127
	v_cvt_pk_bf16_f32 v126, v120, v121
	v_cvt_pk_bf16_f32 v127, v122, v123
	global_store_dwordx4 v[158:159], v[124:127], off
	v_pk_mul_f32 v[116:117], v[116:117], v[150:151] op_sel_hi:[1,0]
	v_pk_mul_f32 v[118:119], v[118:119], v[150:151] op_sel_hi:[1,0]
	v_pk_mul_f32 v[112:113], v[112:113], v[150:151] op_sel_hi:[1,0]
	v_pk_mul_f32 v[114:115], v[114:115], v[150:151] op_sel_hi:[1,0]
	v_cvt_pk_bf16_f32 v116, v116, v117
	v_cvt_pk_bf16_f32 v117, v118, v119
	v_cvt_pk_bf16_f32 v118, v112, v113
	v_cvt_pk_bf16_f32 v119, v114, v115
	global_store_dwordx4 v[158:159], v[116:119], off offset:256
	v_lshl_add_u64 v[158:159], v[158:159], 0, s[28:29]
	v_pk_mul_f32 v[108:109], v[108:109], v[150:151] op_sel:[0,1] op_sel_hi:[1,1]
	v_pk_mul_f32 v[110:111], v[110:111], v[150:151] op_sel:[0,1] op_sel_hi:[1,1]
	v_pk_mul_f32 v[104:105], v[104:105], v[150:151] op_sel:[0,1] op_sel_hi:[1,1]
	v_pk_mul_f32 v[106:107], v[106:107], v[150:151] op_sel:[0,1] op_sel_hi:[1,1]
	v_cvt_pk_bf16_f32 v108, v108, v109
	v_cvt_pk_bf16_f32 v109, v110, v111
	v_cvt_pk_bf16_f32 v110, v104, v105
	v_cvt_pk_bf16_f32 v111, v106, v107
	global_store_dwordx4 v[158:159], v[108:111], off
	v_pk_mul_f32 v[100:101], v[100:101], v[150:151] op_sel:[0,1] op_sel_hi:[1,1]
	v_pk_mul_f32 v[102:103], v[102:103], v[150:151] op_sel:[0,1] op_sel_hi:[1,1]
	v_pk_mul_f32 v[96:97], v[96:97], v[150:151] op_sel:[0,1] op_sel_hi:[1,1]
	v_pk_mul_f32 v[98:99], v[98:99], v[150:151] op_sel:[0,1] op_sel_hi:[1,1]
	v_cvt_pk_bf16_f32 v100, v100, v101
	v_cvt_pk_bf16_f32 v101, v102, v103
	v_cvt_pk_bf16_f32 v102, v96, v97
	v_cvt_pk_bf16_f32 v103, v98, v99
	global_store_dwordx4 v[158:159], v[100:103], off offset:256
	v_lshl_add_u64 v[158:159], v[158:159], 0, s[28:29]
	v_pk_mul_f32 v[92:93], v[92:93], v[152:153] op_sel_hi:[1,0]
	v_pk_mul_f32 v[94:95], v[94:95], v[152:153] op_sel_hi:[1,0]
	v_pk_mul_f32 v[88:89], v[88:89], v[152:153] op_sel_hi:[1,0]
	v_pk_mul_f32 v[90:91], v[90:91], v[152:153] op_sel_hi:[1,0]
	v_cvt_pk_bf16_f32 v92, v92, v93
	v_cvt_pk_bf16_f32 v93, v94, v95
	v_cvt_pk_bf16_f32 v94, v88, v89
	v_cvt_pk_bf16_f32 v95, v90, v91
	global_store_dwordx4 v[158:159], v[92:95], off
	v_pk_mul_f32 v[84:85], v[84:85], v[152:153] op_sel_hi:[1,0]
	v_pk_mul_f32 v[86:87], v[86:87], v[152:153] op_sel_hi:[1,0]
	v_pk_mul_f32 v[80:81], v[80:81], v[152:153] op_sel_hi:[1,0]
	v_pk_mul_f32 v[82:83], v[82:83], v[152:153] op_sel_hi:[1,0]
	v_cvt_pk_bf16_f32 v84, v84, v85
	v_cvt_pk_bf16_f32 v85, v86, v87
	v_cvt_pk_bf16_f32 v86, v80, v81
	v_cvt_pk_bf16_f32 v87, v82, v83
	global_store_dwordx4 v[158:159], v[84:87], off offset:256
	v_lshl_add_u64 v[158:159], v[158:159], 0, s[28:29]
	v_pk_mul_f32 v[76:77], v[76:77], v[152:153] op_sel:[0,1] op_sel_hi:[1,1]
	v_pk_mul_f32 v[78:79], v[78:79], v[152:153] op_sel:[0,1] op_sel_hi:[1,1]
	v_pk_mul_f32 v[72:73], v[72:73], v[152:153] op_sel:[0,1] op_sel_hi:[1,1]
	v_pk_mul_f32 v[74:75], v[74:75], v[152:153] op_sel:[0,1] op_sel_hi:[1,1]
	v_cvt_pk_bf16_f32 v76, v76, v77
	v_cvt_pk_bf16_f32 v77, v78, v79
	v_cvt_pk_bf16_f32 v78, v72, v73
	v_cvt_pk_bf16_f32 v79, v74, v75
	global_store_dwordx4 v[158:159], v[76:79], off
	v_pk_mul_f32 v[68:69], v[68:69], v[152:153] op_sel:[0,1] op_sel_hi:[1,1]
	v_pk_mul_f32 v[70:71], v[70:71], v[152:153] op_sel:[0,1] op_sel_hi:[1,1]
	v_pk_mul_f32 v[64:65], v[64:65], v[152:153] op_sel:[0,1] op_sel_hi:[1,1]
	v_pk_mul_f32 v[66:67], v[66:67], v[152:153] op_sel:[0,1] op_sel_hi:[1,1]
	v_cvt_pk_bf16_f32 v68, v68, v69
	v_cvt_pk_bf16_f32 v69, v70, v71
	v_cvt_pk_bf16_f32 v70, v64, v65
	v_cvt_pk_bf16_f32 v71, v66, v67
	global_store_dwordx4 v[158:159], v[68:71], off offset:256
	v_lshl_add_u64 v[158:159], v[158:159], 0, s[30:31]
	v_pk_mul_f32 v[60:61], v[60:61], v[154:155] op_sel_hi:[1,0]
	v_pk_mul_f32 v[62:63], v[62:63], v[154:155] op_sel_hi:[1,0]
	v_pk_mul_f32 v[56:57], v[56:57], v[154:155] op_sel_hi:[1,0]
	v_pk_mul_f32 v[58:59], v[58:59], v[154:155] op_sel_hi:[1,0]
	v_cvt_pk_bf16_f32 v60, v60, v61
	v_cvt_pk_bf16_f32 v61, v62, v63
	v_cvt_pk_bf16_f32 v62, v56, v57
	v_cvt_pk_bf16_f32 v63, v58, v59
	global_store_dwordx4 v[158:159], v[60:63], off
	v_pk_mul_f32 v[52:53], v[52:53], v[154:155] op_sel_hi:[1,0]
	v_pk_mul_f32 v[54:55], v[54:55], v[154:155] op_sel_hi:[1,0]
	v_pk_mul_f32 v[48:49], v[48:49], v[154:155] op_sel_hi:[1,0]
	v_pk_mul_f32 v[50:51], v[50:51], v[154:155] op_sel_hi:[1,0]
	v_cvt_pk_bf16_f32 v52, v52, v53
	v_cvt_pk_bf16_f32 v53, v54, v55
	v_cvt_pk_bf16_f32 v54, v48, v49
	v_cvt_pk_bf16_f32 v55, v50, v51
	global_store_dwordx4 v[158:159], v[52:55], off offset:256
	v_lshl_add_u64 v[158:159], v[158:159], 0, s[28:29]
	v_pk_mul_f32 v[44:45], v[44:45], v[154:155] op_sel:[0,1] op_sel_hi:[1,1]
	v_pk_mul_f32 v[46:47], v[46:47], v[154:155] op_sel:[0,1] op_sel_hi:[1,1]
	v_pk_mul_f32 v[40:41], v[40:41], v[154:155] op_sel:[0,1] op_sel_hi:[1,1]
	v_pk_mul_f32 v[42:43], v[42:43], v[154:155] op_sel:[0,1] op_sel_hi:[1,1]
	v_cvt_pk_bf16_f32 v44, v44, v45
	v_cvt_pk_bf16_f32 v45, v46, v47
	v_cvt_pk_bf16_f32 v46, v40, v41
	v_cvt_pk_bf16_f32 v47, v42, v43
	global_store_dwordx4 v[158:159], v[44:47], off
	v_pk_mul_f32 v[36:37], v[36:37], v[154:155] op_sel:[0,1] op_sel_hi:[1,1]
	v_pk_mul_f32 v[38:39], v[38:39], v[154:155] op_sel:[0,1] op_sel_hi:[1,1]
	v_pk_mul_f32 v[32:33], v[32:33], v[154:155] op_sel:[0,1] op_sel_hi:[1,1]
	v_pk_mul_f32 v[34:35], v[34:35], v[154:155] op_sel:[0,1] op_sel_hi:[1,1]
	v_cvt_pk_bf16_f32 v36, v36, v37
	v_cvt_pk_bf16_f32 v37, v38, v39
	v_cvt_pk_bf16_f32 v38, v32, v33
	v_cvt_pk_bf16_f32 v39, v34, v35
	global_store_dwordx4 v[158:159], v[36:39], off offset:256
	v_lshl_add_u64 v[158:159], v[158:159], 0, s[28:29]
	v_pk_mul_f32 v[28:29], v[28:29], v[156:157] op_sel_hi:[1,0]
	v_pk_mul_f32 v[30:31], v[30:31], v[156:157] op_sel_hi:[1,0]
	v_pk_mul_f32 v[24:25], v[24:25], v[156:157] op_sel_hi:[1,0]
	v_pk_mul_f32 v[26:27], v[26:27], v[156:157] op_sel_hi:[1,0]
	v_cvt_pk_bf16_f32 v28, v28, v29
	v_cvt_pk_bf16_f32 v29, v30, v31
	v_cvt_pk_bf16_f32 v30, v24, v25
	v_cvt_pk_bf16_f32 v31, v26, v27
	global_store_dwordx4 v[158:159], v[28:31], off
	v_pk_mul_f32 v[20:21], v[20:21], v[156:157] op_sel_hi:[1,0]
	v_pk_mul_f32 v[22:23], v[22:23], v[156:157] op_sel_hi:[1,0]
	v_pk_mul_f32 v[16:17], v[16:17], v[156:157] op_sel_hi:[1,0]
	v_pk_mul_f32 v[18:19], v[18:19], v[156:157] op_sel_hi:[1,0]
	v_cvt_pk_bf16_f32 v20, v20, v21
	v_cvt_pk_bf16_f32 v21, v22, v23
	v_cvt_pk_bf16_f32 v22, v16, v17
	v_cvt_pk_bf16_f32 v23, v18, v19
	global_store_dwordx4 v[158:159], v[20:23], off offset:256
	v_lshl_add_u64 v[158:159], v[158:159], 0, s[28:29]
	v_pk_mul_f32 v[12:13], v[12:13], v[156:157] op_sel:[0,1] op_sel_hi:[1,1]
	v_pk_mul_f32 v[14:15], v[14:15], v[156:157] op_sel:[0,1] op_sel_hi:[1,1]
	v_pk_mul_f32 v[8:9], v[8:9], v[156:157] op_sel:[0,1] op_sel_hi:[1,1]
	v_pk_mul_f32 v[10:11], v[10:11], v[156:157] op_sel:[0,1] op_sel_hi:[1,1]
	v_cvt_pk_bf16_f32 v12, v12, v13
	v_cvt_pk_bf16_f32 v13, v14, v15
	v_cvt_pk_bf16_f32 v14, v8, v9
	v_cvt_pk_bf16_f32 v15, v10, v11
	global_store_dwordx4 v[158:159], v[12:15], off
	v_pk_mul_f32 v[4:5], v[4:5], v[156:157] op_sel:[0,1] op_sel_hi:[1,1]
	v_pk_mul_f32 v[6:7], v[6:7], v[156:157] op_sel:[0,1] op_sel_hi:[1,1]
	v_pk_mul_f32 v[0:1], v[0:1], v[156:157] op_sel:[0,1] op_sel_hi:[1,1]
	v_pk_mul_f32 v[2:3], v[2:3], v[156:157] op_sel:[0,1] op_sel_hi:[1,1]
	v_cvt_pk_bf16_f32 v4, v4, v5
	v_cvt_pk_bf16_f32 v5, v6, v7
	v_cvt_pk_bf16_f32 v6, v0, v1
	v_cvt_pk_bf16_f32 v7, v2, v3
	global_store_dwordx4 v[158:159], v[4:7], off offset:256
	s_branch .Lz_done
.Lz_rope:
	v_and_b32_e32 v162, 0x7ff, v148
	v_and_b32_e32 v163, 63, v189
	v_lshlrev_b32_e32 v162, 7, v162
	v_lshl_add_u32 v162, v163, 1, v162
	v_mov_b32_e32 v163, 0
	v_lshl_add_u64 v[146:147], s[18:19], 0, v[162:163]
	v_lshl_add_u64 v[162:163], s[20:21], 0, v[162:163]
	s_mov_b64 s[28:29], 0x800
	s_mov_b64 s[30:31], 0x2800
	global_load_dwordx4 v[194:197], v[146:147], off
	global_load_dwordx4 v[228:231], v[162:163], off
	v_lshl_add_u64 v[146:147], v[146:147], 0, s[28:29]
	v_lshl_add_u64 v[162:163], v[162:163], 0, s[28:29]
	global_load_dwordx4 v[198:201], v[146:147], off
	global_load_dwordx4 v[232:235], v[162:163], off
	v_lshl_add_u64 v[146:147], v[146:147], 0, s[28:29]
	v_lshl_add_u64 v[162:163], v[162:163], 0, s[28:29]
	global_load_dwordx4 v[202:205], v[146:147], off
	global_load_dwordx4 v[164:167], v[162:163], off
	v_lshl_add_u64 v[146:147], v[146:147], 0, s[28:29]
	v_lshl_add_u64 v[162:163], v[162:163], 0, s[28:29]
	global_load_dwordx4 v[206:209], v[146:147], off
	global_load_dwordx4 v[168:171], v[162:163], off
	v_lshl_add_u64 v[146:147], v[146:147], 0, s[30:31]
	v_lshl_add_u64 v[162:163], v[162:163], 0, s[30:31]
	global_load_dwordx4 v[210:213], v[146:147], off
	global_load_dwordx4 v[172:175], v[162:163], off
	v_lshl_add_u64 v[146:147], v[146:147], 0, s[28:29]
	v_lshl_add_u64 v[162:163], v[162:163], 0, s[28:29]
	global_load_dwordx4 v[216:219], v[146:147], off
	global_load_dwordx4 v[244:247], v[162:163], off
	v_lshl_add_u64 v[146:147], v[146:147], 0, s[28:29]
	v_lshl_add_u64 v[162:163], v[162:163], 0, s[28:29]
	global_load_dwordx4 v[220:223], v[146:147], off
	global_load_dwordx4 v[248:251], v[162:163], off
	v_lshl_add_u64 v[146:147], v[146:147], 0, s[28:29]
	v_lshl_add_u64 v[162:163], v[162:163], 0, s[28:29]
	global_load_dwordx4 v[224:227], v[146:147], off
	global_load_dwordx4 v[252:255], v[162:163], off
	v_lshlrev_b32_e32 v160, 1, v160
	v_lshl_add_u64 v[160:161], s[10:11], 0, v[160:161]
	v_mad_i64_i32 v[158:159], vcc, v148, s62, v[160:161]
	s_mov_b64 s[28:29], 0x18000
	s_mov_b64 s[30:31], 0x78000
	s_waitcnt vmcnt(0)
	v_pk_mul_f32 v[194:195], v[194:195], v[150:151] op_sel_hi:[1,0]
	v_pk_mul_f32 v[196:197], v[196:197], v[150:151] op_sel_hi:[1,0]
	v_pk_mul_f32 v[228:229], v[228:229], v[150:151] op_sel_hi:[1,0]
	v_pk_mul_f32 v[230:231], v[230:231], v[150:151] op_sel_hi:[1,0]
	v_pk_mul_f32 v[160:161], v[124:125], v[228:229] op_sel:[0,0] op_sel_hi:[1,0]
	v_pk_fma_f32 v[124:125], v[124:125], v[194:195], v[160:161] op_sel:[0,0,1] op_sel_hi:[1,0,0] neg_lo:[0,0,1]
	v_pk_mul_f32 v[162:163], v[126:127], v[228:229] op_sel:[0,1] op_sel_hi:[1,1]
	v_pk_fma_f32 v[126:127], v[126:127], v[194:195], v[162:163] op_sel:[0,1,1] op_sel_hi:[1,1,0] neg_lo:[0,0,1]
	v_pk_mul_f32 v[160:161], v[120:121], v[230:231] op_sel:[0,0] op_sel_hi:[1,0]
	v_pk_fma_f32 v[120:121], v[120:121], v[196:197], v[160:161] op_sel:[0,0,1] op_sel_hi:[1,0,0] neg_lo:[0,0,1]
	v_pk_mul_f32 v[162:163], v[122:123], v[230:231] op_sel:[0,1] op_sel_hi:[1,1]
	v_pk_fma_f32 v[122:123], v[122:123], v[196:197], v[162:163] op_sel:[0,1,1] op_sel_hi:[1,1,0] neg_lo:[0,0,1]
	v_cvt_pk_bf16_f32 v124, v124, v125
	v_cvt_pk_bf16_f32 v125, v126, v127
	v_cvt_pk_bf16_f32 v126, v120, v121
	v_cvt_pk_bf16_f32 v127, v122, v123
	global_store_dwordx4 v[158:159], v[124:127], off
	v_pk_mul_f32 v[160:161], v[116:117], v[228:229] op_sel:[0,0] op_sel_hi:[1,0]
	v_pk_fma_f32 v[116:117], v[116:117], v[194:195], v[160:161] op_sel:[0,0,1] op_sel_hi:[1,0,0] neg_lo:[0,0,1]
	v_pk_mul_f32 v[162:163], v[118:119], v[228:229] op_sel:[0,1] op_sel_hi:[1,1]
	v_pk_fma_f32 v[118:119], v[118:119], v[194:195], v[162:163] op_sel:[0,1,1] op_sel_hi:[1,1,0] neg_lo:[0,0,1]
	v_pk_mul_f32 v[160:161], v[112:113], v[230:231] op_sel:[0,0] op_sel_hi:[1,0]
	v_pk_fma_f32 v[112:113], v[112:113], v[196:197], v[160:161] op_sel:[0,0,1] op_sel_hi:[1,0,0] neg_lo:[0,0,1]
	v_pk_mul_f32 v[162:163], v[114:115], v[230:231] op_sel:[0,1] op_sel_hi:[1,1]
	v_pk_fma_f32 v[114:115], v[114:115], v[196:197], v[162:163] op_sel:[0,1,1] op_sel_hi:[1,1,0] neg_lo:[0,0,1]
	v_cvt_pk_bf16_f32 v116, v116, v117
	v_cvt_pk_bf16_f32 v117, v118, v119
	v_cvt_pk_bf16_f32 v118, v112, v113
	v_cvt_pk_bf16_f32 v119, v114, v115
	global_store_dwordx4 v[158:159], v[116:119], off offset:256
	v_lshl_add_u64 v[158:159], v[158:159], 0, s[28:29]
	v_pk_mul_f32 v[198:199], v[198:199], v[150:151] op_sel:[0,1] op_sel_hi:[1,1]
	v_pk_mul_f32 v[200:201], v[200:201], v[150:151] op_sel:[0,1] op_sel_hi:[1,1]
	v_pk_mul_f32 v[232:233], v[232:233], v[150:151] op_sel:[0,1] op_sel_hi:[1,1]
	v_pk_mul_f32 v[234:235], v[234:235], v[150:151] op_sel:[0,1] op_sel_hi:[1,1]
	v_pk_mul_f32 v[160:161], v[108:109], v[232:233] op_sel:[0,0] op_sel_hi:[1,0]
	v_pk_fma_f32 v[108:109], v[108:109], v[198:199], v[160:161] op_sel:[0,0,1] op_sel_hi:[1,0,0] neg_lo:[0,0,1]
	v_pk_mul_f32 v[162:163], v[110:111], v[232:233] op_sel:[0,1] op_sel_hi:[1,1]
	v_pk_fma_f32 v[110:111], v[110:111], v[198:199], v[162:163] op_sel:[0,1,1] op_sel_hi:[1,1,0] neg_lo:[0,0,1]
	v_pk_mul_f32 v[160:161], v[104:105], v[234:235] op_sel:[0,0] op_sel_hi:[1,0]
	v_pk_fma_f32 v[104:105], v[104:105], v[200:201], v[160:161] op_sel:[0,0,1] op_sel_hi:[1,0,0] neg_lo:[0,0,1]
	v_pk_mul_f32 v[162:163], v[106:107], v[234:235] op_sel:[0,1] op_sel_hi:[1,1]
	v_pk_fma_f32 v[106:107], v[106:107], v[200:201], v[162:163] op_sel:[0,1,1] op_sel_hi:[1,1,0] neg_lo:[0,0,1]
	v_cvt_pk_bf16_f32 v108, v108, v109
	v_cvt_pk_bf16_f32 v109, v110, v111
	v_cvt_pk_bf16_f32 v110, v104, v105
	v_cvt_pk_bf16_f32 v111, v106, v107
	global_store_dwordx4 v[158:159], v[108:111], off
	v_pk_mul_f32 v[160:161], v[100:101], v[232:233] op_sel:[0,0] op_sel_hi:[1,0]
	v_pk_fma_f32 v[100:101], v[100:101], v[198:199], v[160:161] op_sel:[0,0,1] op_sel_hi:[1,0,0] neg_lo:[0,0,1]
	v_pk_mul_f32 v[162:163], v[102:103], v[232:233] op_sel:[0,1] op_sel_hi:[1,1]
	v_pk_fma_f32 v[102:103], v[102:103], v[198:199], v[162:163] op_sel:[0,1,1] op_sel_hi:[1,1,0] neg_lo:[0,0,1]
	v_pk_mul_f32 v[160:161], v[96:97], v[234:235] op_sel:[0,0] op_sel_hi:[1,0]
	v_pk_fma_f32 v[96:97], v[96:97], v[200:201], v[160:161] op_sel:[0,0,1] op_sel_hi:[1,0,0] neg_lo:[0,0,1]
	v_pk_mul_f32 v[162:163], v[98:99], v[234:235] op_sel:[0,1] op_sel_hi:[1,1]
	v_pk_fma_f32 v[98:99], v[98:99], v[200:201], v[162:163] op_sel:[0,1,1] op_sel_hi:[1,1,0] neg_lo:[0,0,1]
	v_cvt_pk_bf16_f32 v100, v100, v101
	v_cvt_pk_bf16_f32 v101, v102, v103
	v_cvt_pk_bf16_f32 v102, v96, v97
	v_cvt_pk_bf16_f32 v103, v98, v99
	global_store_dwordx4 v[158:159], v[100:103], off offset:256
	v_lshl_add_u64 v[158:159], v[158:159], 0, s[28:29]
	v_pk_mul_f32 v[202:203], v[202:203], v[152:153] op_sel_hi:[1,0]
	v_pk_mul_f32 v[204:205], v[204:205], v[152:153] op_sel_hi:[1,0]
	v_pk_mul_f32 v[164:165], v[164:165], v[152:153] op_sel_hi:[1,0]
	v_pk_mul_f32 v[166:167], v[166:167], v[152:153] op_sel_hi:[1,0]
	v_pk_mul_f32 v[160:161], v[92:93], v[164:165] op_sel:[0,0] op_sel_hi:[1,0]
	v_pk_fma_f32 v[92:93], v[92:93], v[202:203], v[160:161] op_sel:[0,0,1] op_sel_hi:[1,0,0] neg_lo:[0,0,1]
	v_pk_mul_f32 v[162:163], v[94:95], v[164:165] op_sel:[0,1] op_sel_hi:[1,1]
	v_pk_fma_f32 v[94:95], v[94:95], v[202:203], v[162:163] op_sel:[0,1,1] op_sel_hi:[1,1,0] neg_lo:[0,0,1]
	v_pk_mul_f32 v[160:161], v[88:89], v[166:167] op_sel:[0,0] op_sel_hi:[1,0]
	v_pk_fma_f32 v[88:89], v[88:89], v[204:205], v[160:161] op_sel:[0,0,1] op_sel_hi:[1,0,0] neg_lo:[0,0,1]
	v_pk_mul_f32 v[162:163], v[90:91], v[166:167] op_sel:[0,1] op_sel_hi:[1,1]
	v_pk_fma_f32 v[90:91], v[90:91], v[204:205], v[162:163] op_sel:[0,1,1] op_sel_hi:[1,1,0] neg_lo:[0,0,1]
	v_cvt_pk_bf16_f32 v92, v92, v93
	v_cvt_pk_bf16_f32 v93, v94, v95
	v_cvt_pk_bf16_f32 v94, v88, v89
	v_cvt_pk_bf16_f32 v95, v90, v91
	global_store_dwordx4 v[158:159], v[92:95], off
	v_pk_mul_f32 v[160:161], v[84:85], v[164:165] op_sel:[0,0] op_sel_hi:[1,0]
	v_pk_fma_f32 v[84:85], v[84:85], v[202:203], v[160:161] op_sel:[0,0,1] op_sel_hi:[1,0,0] neg_lo:[0,0,1]
	v_pk_mul_f32 v[162:163], v[86:87], v[164:165] op_sel:[0,1] op_sel_hi:[1,1]
	v_pk_fma_f32 v[86:87], v[86:87], v[202:203], v[162:163] op_sel:[0,1,1] op_sel_hi:[1,1,0] neg_lo:[0,0,1]
	v_pk_mul_f32 v[160:161], v[80:81], v[166:167] op_sel:[0,0] op_sel_hi:[1,0]
	v_pk_fma_f32 v[80:81], v[80:81], v[204:205], v[160:161] op_sel:[0,0,1] op_sel_hi:[1,0,0] neg_lo:[0,0,1]
	v_pk_mul_f32 v[162:163], v[82:83], v[166:167] op_sel:[0,1] op_sel_hi:[1,1]
	v_pk_fma_f32 v[82:83], v[82:83], v[204:205], v[162:163] op_sel:[0,1,1] op_sel_hi:[1,1,0] neg_lo:[0,0,1]
	v_cvt_pk_bf16_f32 v84, v84, v85
	v_cvt_pk_bf16_f32 v85, v86, v87
	v_cvt_pk_bf16_f32 v86, v80, v81
	v_cvt_pk_bf16_f32 v87, v82, v83
	global_store_dwordx4 v[158:159], v[84:87], off offset:256
	v_lshl_add_u64 v[158:159], v[158:159], 0, s[28:29]
	v_pk_mul_f32 v[206:207], v[206:207], v[152:153] op_sel:[0,1] op_sel_hi:[1,1]
	v_pk_mul_f32 v[208:209], v[208:209], v[152:153] op_sel:[0,1] op_sel_hi:[1,1]
	v_pk_mul_f32 v[168:169], v[168:169], v[152:153] op_sel:[0,1] op_sel_hi:[1,1]
	v_pk_mul_f32 v[170:171], v[170:171], v[152:153] op_sel:[0,1] op_sel_hi:[1,1]
	v_pk_mul_f32 v[160:161], v[76:77], v[168:169] op_sel:[0,0] op_sel_hi:[1,0]
	v_pk_fma_f32 v[76:77], v[76:77], v[206:207], v[160:161] op_sel:[0,0,1] op_sel_hi:[1,0,0] neg_lo:[0,0,1]
	v_pk_mul_f32 v[162:163], v[78:79], v[168:169] op_sel:[0,1] op_sel_hi:[1,1]
	v_pk_fma_f32 v[78:79], v[78:79], v[206:207], v[162:163] op_sel:[0,1,1] op_sel_hi:[1,1,0] neg_lo:[0,0,1]
	v_pk_mul_f32 v[160:161], v[72:73], v[170:171] op_sel:[0,0] op_sel_hi:[1,0]
	v_pk_fma_f32 v[72:73], v[72:73], v[208:209], v[160:161] op_sel:[0,0,1] op_sel_hi:[1,0,0] neg_lo:[0,0,1]
	v_pk_mul_f32 v[162:163], v[74:75], v[170:171] op_sel:[0,1] op_sel_hi:[1,1]
	v_pk_fma_f32 v[74:75], v[74:75], v[208:209], v[162:163] op_sel:[0,1,1] op_sel_hi:[1,1,0] neg_lo:[0,0,1]
	v_cvt_pk_bf16_f32 v76, v76, v77
	v_cvt_pk_bf16_f32 v77, v78, v79
	v_cvt_pk_bf16_f32 v78, v72, v73
	v_cvt_pk_bf16_f32 v79, v74, v75
	global_store_dwordx4 v[158:159], v[76:79], off
	v_pk_mul_f32 v[160:161], v[68:69], v[168:169] op_sel:[0,0] op_sel_hi:[1,0]
	v_pk_fma_f32 v[68:69], v[68:69], v[206:207], v[160:161] op_sel:[0,0,1] op_sel_hi:[1,0,0] neg_lo:[0,0,1]
	v_pk_mul_f32 v[162:163], v[70:71], v[168:169] op_sel:[0,1] op_sel_hi:[1,1]
	v_pk_fma_f32 v[70:71], v[70:71], v[206:207], v[162:163] op_sel:[0,1,1] op_sel_hi:[1,1,0] neg_lo:[0,0,1]
	v_pk_mul_f32 v[160:161], v[64:65], v[170:171] op_sel:[0,0] op_sel_hi:[1,0]
	v_pk_fma_f32 v[64:65], v[64:65], v[208:209], v[160:161] op_sel:[0,0,1] op_sel_hi:[1,0,0] neg_lo:[0,0,1]
	v_pk_mul_f32 v[162:163], v[66:67], v[170:171] op_sel:[0,1] op_sel_hi:[1,1]
	v_pk_fma_f32 v[66:67], v[66:67], v[208:209], v[162:163] op_sel:[0,1,1] op_sel_hi:[1,1,0] neg_lo:[0,0,1]
	v_cvt_pk_bf16_f32 v68, v68, v69
	v_cvt_pk_bf16_f32 v69, v70, v71
	v_cvt_pk_bf16_f32 v70, v64, v65
	v_cvt_pk_bf16_f32 v71, v66, v67
	global_store_dwordx4 v[158:159], v[68:71], off offset:256
	v_lshl_add_u64 v[158:159], v[158:159], 0, s[30:31]
	v_pk_mul_f32 v[210:211], v[210:211], v[154:155] op_sel_hi:[1,0]
	v_pk_mul_f32 v[212:213], v[212:213], v[154:155] op_sel_hi:[1,0]
	v_pk_mul_f32 v[172:173], v[172:173], v[154:155] op_sel_hi:[1,0]
	v_pk_mul_f32 v[174:175], v[174:175], v[154:155] op_sel_hi:[1,0]
	v_pk_mul_f32 v[160:161], v[60:61], v[172:173] op_sel:[0,0] op_sel_hi:[1,0]
	v_pk_fma_f32 v[60:61], v[60:61], v[210:211], v[160:161] op_sel:[0,0,1] op_sel_hi:[1,0,0] neg_lo:[0,0,1]
	v_pk_mul_f32 v[162:163], v[62:63], v[172:173] op_sel:[0,1] op_sel_hi:[1,1]
	v_pk_fma_f32 v[62:63], v[62:63], v[210:211], v[162:163] op_sel:[0,1,1] op_sel_hi:[1,1,0] neg_lo:[0,0,1]
	v_pk_mul_f32 v[160:161], v[56:57], v[174:175] op_sel:[0,0] op_sel_hi:[1,0]
	v_pk_fma_f32 v[56:57], v[56:57], v[212:213], v[160:161] op_sel:[0,0,1] op_sel_hi:[1,0,0] neg_lo:[0,0,1]
	v_pk_mul_f32 v[162:163], v[58:59], v[174:175] op_sel:[0,1] op_sel_hi:[1,1]
	v_pk_fma_f32 v[58:59], v[58:59], v[212:213], v[162:163] op_sel:[0,1,1] op_sel_hi:[1,1,0] neg_lo:[0,0,1]
	v_cvt_pk_bf16_f32 v60, v60, v61
	v_cvt_pk_bf16_f32 v61, v62, v63
	v_cvt_pk_bf16_f32 v62, v56, v57
	v_cvt_pk_bf16_f32 v63, v58, v59
	global_store_dwordx4 v[158:159], v[60:63], off
	v_pk_mul_f32 v[160:161], v[52:53], v[172:173] op_sel:[0,0] op_sel_hi:[1,0]
	v_pk_fma_f32 v[52:53], v[52:53], v[210:211], v[160:161] op_sel:[0,0,1] op_sel_hi:[1,0,0] neg_lo:[0,0,1]
	v_pk_mul_f32 v[162:163], v[54:55], v[172:173] op_sel:[0,1] op_sel_hi:[1,1]
	v_pk_fma_f32 v[54:55], v[54:55], v[210:211], v[162:163] op_sel:[0,1,1] op_sel_hi:[1,1,0] neg_lo:[0,0,1]
	v_pk_mul_f32 v[160:161], v[48:49], v[174:175] op_sel:[0,0] op_sel_hi:[1,0]
	v_pk_fma_f32 v[48:49], v[48:49], v[212:213], v[160:161] op_sel:[0,0,1] op_sel_hi:[1,0,0] neg_lo:[0,0,1]
	v_pk_mul_f32 v[162:163], v[50:51], v[174:175] op_sel:[0,1] op_sel_hi:[1,1]
	v_pk_fma_f32 v[50:51], v[50:51], v[212:213], v[162:163] op_sel:[0,1,1] op_sel_hi:[1,1,0] neg_lo:[0,0,1]
	v_cvt_pk_bf16_f32 v52, v52, v53
	v_cvt_pk_bf16_f32 v53, v54, v55
	v_cvt_pk_bf16_f32 v54, v48, v49
	v_cvt_pk_bf16_f32 v55, v50, v51
	global_store_dwordx4 v[158:159], v[52:55], off offset:256
	v_lshl_add_u64 v[158:159], v[158:159], 0, s[28:29]
	v_pk_mul_f32 v[216:217], v[216:217], v[154:155] op_sel:[0,1] op_sel_hi:[1,1]
	v_pk_mul_f32 v[218:219], v[218:219], v[154:155] op_sel:[0,1] op_sel_hi:[1,1]
	v_pk_mul_f32 v[244:245], v[244:245], v[154:155] op_sel:[0,1] op_sel_hi:[1,1]
	v_pk_mul_f32 v[246:247], v[246:247], v[154:155] op_sel:[0,1] op_sel_hi:[1,1]
	v_pk_mul_f32 v[160:161], v[44:45], v[244:245] op_sel:[0,0] op_sel_hi:[1,0]
	v_pk_fma_f32 v[44:45], v[44:45], v[216:217], v[160:161] op_sel:[0,0,1] op_sel_hi:[1,0,0] neg_lo:[0,0,1]
	v_pk_mul_f32 v[162:163], v[46:47], v[244:245] op_sel:[0,1] op_sel_hi:[1,1]
	v_pk_fma_f32 v[46:47], v[46:47], v[216:217], v[162:163] op_sel:[0,1,1] op_sel_hi:[1,1,0] neg_lo:[0,0,1]
	v_pk_mul_f32 v[160:161], v[40:41], v[246:247] op_sel:[0,0] op_sel_hi:[1,0]
	v_pk_fma_f32 v[40:41], v[40:41], v[218:219], v[160:161] op_sel:[0,0,1] op_sel_hi:[1,0,0] neg_lo:[0,0,1]
	v_pk_mul_f32 v[162:163], v[42:43], v[246:247] op_sel:[0,1] op_sel_hi:[1,1]
	v_pk_fma_f32 v[42:43], v[42:43], v[218:219], v[162:163] op_sel:[0,1,1] op_sel_hi:[1,1,0] neg_lo:[0,0,1]
	v_cvt_pk_bf16_f32 v44, v44, v45
	v_cvt_pk_bf16_f32 v45, v46, v47
	v_cvt_pk_bf16_f32 v46, v40, v41
	v_cvt_pk_bf16_f32 v47, v42, v43
	global_store_dwordx4 v[158:159], v[44:47], off
	v_pk_mul_f32 v[160:161], v[36:37], v[244:245] op_sel:[0,0] op_sel_hi:[1,0]
	v_pk_fma_f32 v[36:37], v[36:37], v[216:217], v[160:161] op_sel:[0,0,1] op_sel_hi:[1,0,0] neg_lo:[0,0,1]
	v_pk_mul_f32 v[162:163], v[38:39], v[244:245] op_sel:[0,1] op_sel_hi:[1,1]
	v_pk_fma_f32 v[38:39], v[38:39], v[216:217], v[162:163] op_sel:[0,1,1] op_sel_hi:[1,1,0] neg_lo:[0,0,1]
	v_pk_mul_f32 v[160:161], v[32:33], v[246:247] op_sel:[0,0] op_sel_hi:[1,0]
	v_pk_fma_f32 v[32:33], v[32:33], v[218:219], v[160:161] op_sel:[0,0,1] op_sel_hi:[1,0,0] neg_lo:[0,0,1]
	v_pk_mul_f32 v[162:163], v[34:35], v[246:247] op_sel:[0,1] op_sel_hi:[1,1]
	v_pk_fma_f32 v[34:35], v[34:35], v[218:219], v[162:163] op_sel:[0,1,1] op_sel_hi:[1,1,0] neg_lo:[0,0,1]
	v_cvt_pk_bf16_f32 v36, v36, v37
	v_cvt_pk_bf16_f32 v37, v38, v39
	v_cvt_pk_bf16_f32 v38, v32, v33
	v_cvt_pk_bf16_f32 v39, v34, v35
	global_store_dwordx4 v[158:159], v[36:39], off offset:256
	v_lshl_add_u64 v[158:159], v[158:159], 0, s[28:29]
	v_pk_mul_f32 v[220:221], v[220:221], v[156:157] op_sel_hi:[1,0]
	v_pk_mul_f32 v[222:223], v[222:223], v[156:157] op_sel_hi:[1,0]
	v_pk_mul_f32 v[248:249], v[248:249], v[156:157] op_sel_hi:[1,0]
	v_pk_mul_f32 v[250:251], v[250:251], v[156:157] op_sel_hi:[1,0]
	v_pk_mul_f32 v[160:161], v[28:29], v[248:249] op_sel:[0,0] op_sel_hi:[1,0]
	v_pk_fma_f32 v[28:29], v[28:29], v[220:221], v[160:161] op_sel:[0,0,1] op_sel_hi:[1,0,0] neg_lo:[0,0,1]
	v_pk_mul_f32 v[162:163], v[30:31], v[248:249] op_sel:[0,1] op_sel_hi:[1,1]
	v_pk_fma_f32 v[30:31], v[30:31], v[220:221], v[162:163] op_sel:[0,1,1] op_sel_hi:[1,1,0] neg_lo:[0,0,1]
	v_pk_mul_f32 v[160:161], v[24:25], v[250:251] op_sel:[0,0] op_sel_hi:[1,0]
	v_pk_fma_f32 v[24:25], v[24:25], v[222:223], v[160:161] op_sel:[0,0,1] op_sel_hi:[1,0,0] neg_lo:[0,0,1]
	v_pk_mul_f32 v[162:163], v[26:27], v[250:251] op_sel:[0,1] op_sel_hi:[1,1]
	v_pk_fma_f32 v[26:27], v[26:27], v[222:223], v[162:163] op_sel:[0,1,1] op_sel_hi:[1,1,0] neg_lo:[0,0,1]
	v_cvt_pk_bf16_f32 v28, v28, v29
	v_cvt_pk_bf16_f32 v29, v30, v31
	v_cvt_pk_bf16_f32 v30, v24, v25
	v_cvt_pk_bf16_f32 v31, v26, v27
	global_store_dwordx4 v[158:159], v[28:31], off
	v_pk_mul_f32 v[160:161], v[20:21], v[248:249] op_sel:[0,0] op_sel_hi:[1,0]
	v_pk_fma_f32 v[20:21], v[20:21], v[220:221], v[160:161] op_sel:[0,0,1] op_sel_hi:[1,0,0] neg_lo:[0,0,1]
	v_pk_mul_f32 v[162:163], v[22:23], v[248:249] op_sel:[0,1] op_sel_hi:[1,1]
	v_pk_fma_f32 v[22:23], v[22:23], v[220:221], v[162:163] op_sel:[0,1,1] op_sel_hi:[1,1,0] neg_lo:[0,0,1]
	v_pk_mul_f32 v[160:161], v[16:17], v[250:251] op_sel:[0,0] op_sel_hi:[1,0]
	v_pk_fma_f32 v[16:17], v[16:17], v[222:223], v[160:161] op_sel:[0,0,1] op_sel_hi:[1,0,0] neg_lo:[0,0,1]
	v_pk_mul_f32 v[162:163], v[18:19], v[250:251] op_sel:[0,1] op_sel_hi:[1,1]
	v_pk_fma_f32 v[18:19], v[18:19], v[222:223], v[162:163] op_sel:[0,1,1] op_sel_hi:[1,1,0] neg_lo:[0,0,1]
	v_cvt_pk_bf16_f32 v20, v20, v21
	v_cvt_pk_bf16_f32 v21, v22, v23
	v_cvt_pk_bf16_f32 v22, v16, v17
	v_cvt_pk_bf16_f32 v23, v18, v19
	global_store_dwordx4 v[158:159], v[20:23], off offset:256
	v_lshl_add_u64 v[158:159], v[158:159], 0, s[28:29]
	v_pk_mul_f32 v[224:225], v[224:225], v[156:157] op_sel:[0,1] op_sel_hi:[1,1]
	v_pk_mul_f32 v[226:227], v[226:227], v[156:157] op_sel:[0,1] op_sel_hi:[1,1]
	v_pk_mul_f32 v[252:253], v[252:253], v[156:157] op_sel:[0,1] op_sel_hi:[1,1]
	v_pk_mul_f32 v[254:255], v[254:255], v[156:157] op_sel:[0,1] op_sel_hi:[1,1]
	v_pk_mul_f32 v[160:161], v[12:13], v[252:253] op_sel:[0,0] op_sel_hi:[1,0]
	v_pk_fma_f32 v[12:13], v[12:13], v[224:225], v[160:161] op_sel:[0,0,1] op_sel_hi:[1,0,0] neg_lo:[0,0,1]
	v_pk_mul_f32 v[162:163], v[14:15], v[252:253] op_sel:[0,1] op_sel_hi:[1,1]
	v_pk_fma_f32 v[14:15], v[14:15], v[224:225], v[162:163] op_sel:[0,1,1] op_sel_hi:[1,1,0] neg_lo:[0,0,1]
	v_pk_mul_f32 v[160:161], v[8:9], v[254:255] op_sel:[0,0] op_sel_hi:[1,0]
	v_pk_fma_f32 v[8:9], v[8:9], v[226:227], v[160:161] op_sel:[0,0,1] op_sel_hi:[1,0,0] neg_lo:[0,0,1]
	v_pk_mul_f32 v[162:163], v[10:11], v[254:255] op_sel:[0,1] op_sel_hi:[1,1]
	v_pk_fma_f32 v[10:11], v[10:11], v[226:227], v[162:163] op_sel:[0,1,1] op_sel_hi:[1,1,0] neg_lo:[0,0,1]
	v_cvt_pk_bf16_f32 v12, v12, v13
	v_cvt_pk_bf16_f32 v13, v14, v15
	v_cvt_pk_bf16_f32 v14, v8, v9
	v_cvt_pk_bf16_f32 v15, v10, v11
	global_store_dwordx4 v[158:159], v[12:15], off
	v_pk_mul_f32 v[160:161], v[4:5], v[252:253] op_sel:[0,0] op_sel_hi:[1,0]
	v_pk_fma_f32 v[4:5], v[4:5], v[224:225], v[160:161] op_sel:[0,0,1] op_sel_hi:[1,0,0] neg_lo:[0,0,1]
	v_pk_mul_f32 v[162:163], v[6:7], v[252:253] op_sel:[0,1] op_sel_hi:[1,1]
	v_pk_fma_f32 v[6:7], v[6:7], v[224:225], v[162:163] op_sel:[0,1,1] op_sel_hi:[1,1,0] neg_lo:[0,0,1]
	v_pk_mul_f32 v[160:161], v[0:1], v[254:255] op_sel:[0,0] op_sel_hi:[1,0]
	v_pk_fma_f32 v[0:1], v[0:1], v[226:227], v[160:161] op_sel:[0,0,1] op_sel_hi:[1,0,0] neg_lo:[0,0,1]
	v_pk_mul_f32 v[162:163], v[2:3], v[254:255] op_sel:[0,1] op_sel_hi:[1,1]
	v_pk_fma_f32 v[2:3], v[2:3], v[226:227], v[162:163] op_sel:[0,1,1] op_sel_hi:[1,1,0] neg_lo:[0,0,1]
	v_cvt_pk_bf16_f32 v4, v4, v5
	v_cvt_pk_bf16_f32 v5, v6, v7
	v_cvt_pk_bf16_f32 v6, v0, v1
	v_cvt_pk_bf16_f32 v7, v2, v3
	global_store_dwordx4 v[158:159], v[4:7], off offset:256
.Lz_done:
	s_andn2_b64 vcc, exec, s[2:3]
	s_mov_b64 s[2:3], -1
	s_cbranch_vccnz .LBB0_154
.LBB0_258:
	s_andn2_b64 vcc, exec, s[16:17]
	s_cbranch_vccnz .LBB0_153
	s_barrier
	s_branch .LBB0_153
